# static priority raise moved to the older half of the workgroup (waves 0-3) during the attention items
# speedup vs baseline: 1.0007x; 1.0007x over previous
; DI void phase_attn(const Params& p, char* lds, int l) {
;     ...
;   if (__builtin_amdgcn_readfirstlane(threadIdx.x) >= 256) __builtin_amdgcn_s_setprio(1);
.LBB0_715:
	s_or_b64 exec, exec, s[4:5]
	v_readfirstlane_b32 s4, v199
	s_cmpk_ge_i32 s4, 0x100
	s_cbranch_scc1 .LBB0_717
	s_setprio 1
